# speedup vs baseline: 1.0129x; 1.0017x over previous
; __device__ __forceinline__ void unwiden16(const i32x4 w, u32x2& g0, u32x2& g1) {
;   auto r0 = __builtin_amdgcn_permlane16_swap((unsigned)w[0], (unsigned)w[2], false, false);
;   auto r1 = __builtin_amdgcn_permlane16_swap((unsigned)w[1], (unsigned)w[3], false, false);
;   g0[0] = r0[0]; g0[1] = r1[0]; g1[0] = r0[1]; g1[1] = r1[1];
; }
; template <int EPI, int MB, int NB> ...
;     ...
;     for (int m = 0; m < MB; ++m) {
;       const int lr = lrow0 + m * 16;
;       float sq = 0.f;
;       u32x2 ob[2], rw[2];
;       if (rb) unwiden16(*(const i32x4*)(e.resb + (size_t)(brow + lr) * DM + colw), rw[0], rw[1]);
.LBB0_435:
	v_mov_b32_e32 v146, v209
	v_mov_b32_e32 v112, v210
	s_and_b64 vcc, exec, s[14:15]
	v_add_u32_e32 v144, s66, v112
	v_add_u32_e32 v142, v144, v211
	v_ashrrev_i32_e32 v143, 31, v142
	v_add_u32_e32 v148, s64, v146
	s_cbranch_vccz .LBB0_437
	v_ashrrev_i32_e32 v149, 31, v148
	v_lshlrev_b64 v[112:113], 12, v[148:149]
	v_lshl_add_u64 v[112:113], s[54:55], 0, v[112:113]
	v_lshl_add_u64 v[112:113], v[142:143], 1, v[112:113]
	v_mov_b32_e32 v252, 0x10000
	v_mov_b32_e32 v253, 0
	global_load_dwordx4 v[232:235], v[112:113], off
	v_lshl_add_u64 v[248:249], v[112:113], 0, v[252:253]
	global_load_dwordx4 v[236:239], v[248:249], off
	v_lshl_add_u64 v[248:249], v[248:249], 0, v[252:253]
	global_load_dwordx4 v[240:243], v[248:249], off
	v_lshl_add_u64 v[248:249], v[248:249], 0, v[252:253]
	global_load_dwordx4 v[244:247], v[248:249], off
	s_waitcnt vmcnt(3)
	v_mov_b32_e32 v114, v232
	v_mov_b32_e32 v115, v233
	v_mov_b32_e32 v116, v234
	v_mov_b32_e32 v117, v235
	v_mov_b32_e32 v112, v116
	v_mov_b32_e32 v113, v117
	s_nop 0
	v_permlane16_swap_b32_e32 v114, v112
	v_permlane16_swap_b32_e32 v115, v113
	s_branch .LBB0_438

; __device__ __forceinline__ void unwiden16(const i32x4 w, u32x2& g0, u32x2& g1) {
;   auto r0 = __builtin_amdgcn_permlane16_swap((unsigned)w[0], (unsigned)w[2], false, false);
;   auto r1 = __builtin_amdgcn_permlane16_swap((unsigned)w[1], (unsigned)w[3], false, false);
;   g0[0] = r0[0]; g0[1] = r1[0]; g1[0] = r0[1]; g1[1] = r1[1];
; }
; template <int EPI, int MB, int NB> ...
;     ...
;     for (int m = 0; m < MB; ++m) {
;       const int lr = lrow0 + m * 16;
;       float sq = 0.f;
;       u32x2 ob[2], rw[2];
;       if (rb) unwiden16(*(const i32x4*)(e.resb + (size_t)(brow + lr) * DM + colw), rw[0], rw[1]);
.LBB0_448:
	s_or_b64 exec, exec, s[70:71]
	v_add_u32_e32 v130, 16, v146
	s_and_b64 vcc, exec, s[12:13]
	v_add_u32_e32 v134, s64, v130
	s_cbranch_vccnz .LBB0_450
	v_ashrrev_i32_e32 v135, 31, v134
	v_lshlrev_b64 v[112:113], 12, v[134:135]
	v_lshl_add_u64 v[112:113], s[54:55], 0, v[112:113]
	v_lshl_add_u64 v[112:113], v[142:143], 1, v[112:113]
	s_waitcnt lgkmcnt(0)
	s_waitcnt vmcnt(3)
	v_mov_b32_e32 v114, v236
	v_mov_b32_e32 v115, v237
	v_mov_b32_e32 v116, v238
	v_mov_b32_e32 v117, v239
	v_mov_b32_e32 v112, v116
	v_mov_b32_e32 v113, v117
	s_nop 0
	v_permlane16_swap_b32_e32 v114, v112
	v_permlane16_swap_b32_e32 v115, v113

; __device__ __forceinline__ void unwiden16(const i32x4 w, u32x2& g0, u32x2& g1) {
;   auto r0 = __builtin_amdgcn_permlane16_swap((unsigned)w[0], (unsigned)w[2], false, false);
;   auto r1 = __builtin_amdgcn_permlane16_swap((unsigned)w[1], (unsigned)w[3], false, false);
;   g0[0] = r0[0]; g0[1] = r1[0]; g1[0] = r0[1]; g1[1] = r1[1];
; }
; template <int EPI, int MB, int NB> ...
;     ...
;     for (int m = 0; m < MB; ++m) {
;       const int lr = lrow0 + m * 16;
;       float sq = 0.f;
;       u32x2 ob[2], rw[2];
;       if (rb) unwiden16(*(const i32x4*)(e.resb + (size_t)(brow + lr) * DM + colw), rw[0], rw[1]);
.LBB0_461:
	s_or_b64 exec, exec, s[70:71]
	v_add_u32_e32 v120, 32, v146
	s_and_b64 vcc, exec, s[12:13]
	v_add_u32_e32 v124, s64, v120
	s_cbranch_vccnz .LBB0_463
	v_ashrrev_i32_e32 v125, 31, v124
	v_lshlrev_b64 v[112:113], 12, v[124:125]
	v_lshl_add_u64 v[112:113], s[54:55], 0, v[112:113]
	v_lshl_add_u64 v[112:113], v[142:143], 1, v[112:113]
	s_waitcnt lgkmcnt(0)
	s_waitcnt vmcnt(3)
	v_mov_b32_e32 v114, v240
	v_mov_b32_e32 v115, v241
	v_mov_b32_e32 v116, v242
	v_mov_b32_e32 v117, v243
	v_mov_b32_e32 v112, v116
	v_mov_b32_e32 v113, v117
	s_nop 0
	v_permlane16_swap_b32_e32 v114, v112
	v_permlane16_swap_b32_e32 v115, v113

; __device__ __forceinline__ void unwiden16(const i32x4 w, u32x2& g0, u32x2& g1) {
;   auto r0 = __builtin_amdgcn_permlane16_swap((unsigned)w[0], (unsigned)w[2], false, false);
;   auto r1 = __builtin_amdgcn_permlane16_swap((unsigned)w[1], (unsigned)w[3], false, false);
;   g0[0] = r0[0]; g0[1] = r1[0]; g1[0] = r0[1]; g1[1] = r1[1];
; }
; template <int EPI, int MB, int NB> ...
;     ...
;     for (int m = 0; m < MB; ++m) {
;       const int lr = lrow0 + m * 16;
;       float sq = 0.f;
;       u32x2 ob[2], rw[2];
;       if (rb) unwiden16(*(const i32x4*)(e.resb + (size_t)(brow + lr) * DM + colw), rw[0], rw[1]);
.LBB0_474:
	s_or_b64 exec, exec, s[70:71]
	v_add_u32_e32 v108, 48, v146
	s_and_b64 vcc, exec, s[12:13]
	v_add_u32_e32 v118, s64, v108
	s_cbranch_vccnz .LBB0_476
	v_ashrrev_i32_e32 v119, 31, v118
	s_waitcnt lgkmcnt(0)
	v_lshlrev_b64 v[104:105], 12, v[118:119]
	v_lshl_add_u64 v[104:105], s[54:55], 0, v[104:105]
	v_lshl_add_u64 v[104:105], v[142:143], 1, v[104:105]
	s_waitcnt vmcnt(3)
	v_mov_b32_e32 v114, v244
	v_mov_b32_e32 v115, v245
	v_mov_b32_e32 v116, v246
	v_mov_b32_e32 v117, v247
	v_mov_b32_e32 v104, v116
	v_mov_b32_e32 v105, v117
	s_nop 0
	v_permlane16_swap_b32_e32 v114, v104
	v_permlane16_swap_b32_e32 v115, v105
	v_mov_b32_e32 v112, v104
	v_mov_b32_e32 v113, v105

; __device__ __forceinline__ void unwiden16(const i32x4 w, u32x2& g0, u32x2& g1) {
;   auto r0 = __builtin_amdgcn_permlane16_swap((unsigned)w[0], (unsigned)w[2], false, false);
;   auto r1 = __builtin_amdgcn_permlane16_swap((unsigned)w[1], (unsigned)w[3], false, false);
;   g0[0] = r0[0]; g0[1] = r1[0]; g1[0] = r0[1]; g1[1] = r1[1];
; }
; template <int EPI, int MB, int NB> ...
;     ...
;     for (int m = 0; m < MB; ++m) {
;       const int lr = lrow0 + m * 16;
;       float sq = 0.f;
;       u32x2 ob[2], rw[2];
;       if (rb) unwiden16(*(const i32x4*)(e.resb + (size_t)(brow + lr) * DM + colw), rw[0], rw[1]);
.LBB0_487:
	s_or_b64 exec, exec, s[70:71]
	v_mov_b32_e32 v96, v212
	v_mov_b32_e32 v112, v209
	s_and_b64 vcc, exec, s[12:13]
	v_add_u32_e32 v110, s66, v96
	v_add_u32_e32 v108, v110, v211
	v_ashrrev_i32_e32 v109, 31, v108
	v_add_u32_e32 v114, s64, v112
	s_cbranch_vccnz .LBB0_491
	v_ashrrev_i32_e32 v115, 31, v114
	s_waitcnt lgkmcnt(0)
	v_lshlrev_b64 v[96:97], 12, v[114:115]
	v_lshl_add_u64 v[96:97], s[54:55], 0, v[96:97]
	v_lshl_add_u64 v[96:97], v[108:109], 1, v[96:97]
	v_mov_b32_e32 v252, 0x10000
	v_mov_b32_e32 v253, 0
	global_load_dwordx4 v[232:235], v[96:97], off
	v_lshl_add_u64 v[248:249], v[96:97], 0, v[252:253]
	global_load_dwordx4 v[236:239], v[248:249], off
	v_lshl_add_u64 v[248:249], v[248:249], 0, v[252:253]
	global_load_dwordx4 v[240:243], v[248:249], off
	v_lshl_add_u64 v[248:249], v[248:249], 0, v[252:253]
	global_load_dwordx4 v[244:247], v[248:249], off
	s_waitcnt vmcnt(3)
	v_mov_b32_e32 v98, v232
	v_mov_b32_e32 v99, v233
	v_mov_b32_e32 v100, v234
	v_mov_b32_e32 v101, v235
	v_mov_b32_e32 v96, v100
	v_mov_b32_e32 v97, v101
	s_nop 0
	v_permlane16_swap_b32_e32 v98, v96
	v_permlane16_swap_b32_e32 v99, v97
	s_and_b64 vcc, exec, s[12:13]
	s_cbranch_vccnz .LBB0_492

; __device__ __forceinline__ void unwiden16(const i32x4 w, u32x2& g0, u32x2& g1) {
;   auto r0 = __builtin_amdgcn_permlane16_swap((unsigned)w[0], (unsigned)w[2], false, false);
;   auto r1 = __builtin_amdgcn_permlane16_swap((unsigned)w[1], (unsigned)w[3], false, false);
;   g0[0] = r0[0]; g0[1] = r1[0]; g1[0] = r0[1]; g1[1] = r1[1];
; }
; template <int EPI, int MB, int NB> ...
;     ...
;     for (int m = 0; m < MB; ++m) {
;       const int lr = lrow0 + m * 16;
;       float sq = 0.f;
;       u32x2 ob[2], rw[2];
;       if (rb) unwiden16(*(const i32x4*)(e.resb + (size_t)(brow + lr) * DM + colw), rw[0], rw[1]);
.LBB0_500:
	s_or_b64 exec, exec, s[70:71]
	v_add_u32_e32 v92, 16, v112
	s_and_b64 vcc, exec, s[12:13]
	v_add_u32_e32 v102, s64, v92
	s_cbranch_vccnz .LBB0_502
	v_ashrrev_i32_e32 v103, 31, v102
	s_waitcnt lgkmcnt(0)
	v_lshlrev_b64 v[88:89], 12, v[102:103]
	v_lshl_add_u64 v[88:89], s[54:55], 0, v[88:89]
	v_lshl_add_u64 v[88:89], v[108:109], 1, v[88:89]
	s_waitcnt vmcnt(3)
	v_mov_b32_e32 v98, v236
	v_mov_b32_e32 v99, v237
	v_mov_b32_e32 v100, v238
	v_mov_b32_e32 v101, v239
	v_mov_b32_e32 v88, v100
	v_mov_b32_e32 v89, v101
	s_nop 0
	v_permlane16_swap_b32_e32 v98, v88
	v_permlane16_swap_b32_e32 v99, v89
	v_mov_b32_e32 v96, v88
	v_mov_b32_e32 v97, v89

; __device__ __forceinline__ void unwiden16(const i32x4 w, u32x2& g0, u32x2& g1) {
;   auto r0 = __builtin_amdgcn_permlane16_swap((unsigned)w[0], (unsigned)w[2], false, false);
;   auto r1 = __builtin_amdgcn_permlane16_swap((unsigned)w[1], (unsigned)w[3], false, false);
;   g0[0] = r0[0]; g0[1] = r1[0]; g1[0] = r0[1]; g1[1] = r1[1];
; }
; template <int EPI, int MB, int NB> ...
;     ...
;     for (int m = 0; m < MB; ++m) {
;       const int lr = lrow0 + m * 16;
;       float sq = 0.f;
;       u32x2 ob[2], rw[2];
;       if (rb) unwiden16(*(const i32x4*)(e.resb + (size_t)(brow + lr) * DM + colw), rw[0], rw[1]);
.LBB0_513:
	s_or_b64 exec, exec, s[70:71]
	v_add_u32_e32 v84, 32, v112
	s_and_b64 vcc, exec, s[12:13]
	v_add_u32_e32 v88, s64, v84
	s_cbranch_vccnz .LBB0_515
	v_ashrrev_i32_e32 v89, 31, v88
	s_waitcnt lgkmcnt(0)
	v_lshlrev_b64 v[80:81], 12, v[88:89]
	v_lshl_add_u64 v[80:81], s[54:55], 0, v[80:81]
	v_lshl_add_u64 v[80:81], v[108:109], 1, v[80:81]
	s_waitcnt vmcnt(3)
	v_mov_b32_e32 v98, v240
	v_mov_b32_e32 v99, v241
	v_mov_b32_e32 v100, v242
	v_mov_b32_e32 v101, v243
	v_mov_b32_e32 v80, v100
	v_mov_b32_e32 v81, v101
	s_nop 0
	v_permlane16_swap_b32_e32 v98, v80
	v_permlane16_swap_b32_e32 v99, v81
	v_mov_b32_e32 v96, v80
	v_mov_b32_e32 v97, v81

; __device__ __forceinline__ void unwiden16(const i32x4 w, u32x2& g0, u32x2& g1) {
;   auto r0 = __builtin_amdgcn_permlane16_swap((unsigned)w[0], (unsigned)w[2], false, false);
;   auto r1 = __builtin_amdgcn_permlane16_swap((unsigned)w[1], (unsigned)w[3], false, false);
;   g0[0] = r0[0]; g0[1] = r1[0]; g1[0] = r0[1]; g1[1] = r1[1];
; }
; template <int EPI, int MB, int NB> ...
;     ...
;     for (int m = 0; m < MB; ++m) {
;       const int lr = lrow0 + m * 16;
;       float sq = 0.f;
;       u32x2 ob[2], rw[2];
;       if (rb) unwiden16(*(const i32x4*)(e.resb + (size_t)(brow + lr) * DM + colw), rw[0], rw[1]);
.LBB0_526:
	s_or_b64 exec, exec, s[70:71]
	v_add_u32_e32 v76, 48, v112
	s_and_b64 vcc, exec, s[12:13]
	v_add_u32_e32 v80, s64, v76
	s_cbranch_vccnz .LBB0_528
	v_ashrrev_i32_e32 v81, 31, v80
	s_waitcnt lgkmcnt(0)
	v_lshlrev_b64 v[72:73], 12, v[80:81]
	v_lshl_add_u64 v[72:73], s[54:55], 0, v[72:73]
	v_lshl_add_u64 v[72:73], v[108:109], 1, v[72:73]
	s_waitcnt vmcnt(3)
	v_mov_b32_e32 v98, v244
	v_mov_b32_e32 v99, v245
	v_mov_b32_e32 v100, v246
	v_mov_b32_e32 v101, v247
	v_mov_b32_e32 v72, v100
	v_mov_b32_e32 v73, v101
	s_nop 0
	v_permlane16_swap_b32_e32 v98, v72
	v_permlane16_swap_b32_e32 v99, v73
	v_mov_b32_e32 v96, v72
	v_mov_b32_e32 v97, v73

; __device__ __forceinline__ void unwiden16(const i32x4 w, u32x2& g0, u32x2& g1) {
;   auto r0 = __builtin_amdgcn_permlane16_swap((unsigned)w[0], (unsigned)w[2], false, false);
;   auto r1 = __builtin_amdgcn_permlane16_swap((unsigned)w[1], (unsigned)w[3], false, false);
;   g0[0] = r0[0]; g0[1] = r1[0]; g1[0] = r0[1]; g1[1] = r1[1];
; }
; template <int EPI, int MB, int NB> ...
;     ...
;     for (int m = 0; m < MB; ++m) {
;       const int lr = lrow0 + m * 16;
;       float sq = 0.f;
;       u32x2 ob[2], rw[2];
;       if (rb) unwiden16(*(const i32x4*)(e.resb + (size_t)(brow + lr) * DM + colw), rw[0], rw[1]);
.LBB0_539:
	s_or_b64 exec, exec, s[70:71]
	v_mov_b32_e32 v64, v210
	v_mov_b32_e32 v80, v213
	s_and_b64 vcc, exec, s[12:13]
	v_add_u32_e32 v78, s66, v64
	v_add_u32_e32 v76, v78, v211
	v_ashrrev_i32_e32 v77, 31, v76
	v_add_u32_e32 v82, s64, v80
	s_cbranch_vccnz .LBB0_543
	v_ashrrev_i32_e32 v83, 31, v82
	s_waitcnt lgkmcnt(0)
	v_lshlrev_b64 v[64:65], 12, v[82:83]
	v_lshl_add_u64 v[64:65], s[54:55], 0, v[64:65]
	v_lshl_add_u64 v[64:65], v[76:77], 1, v[64:65]
	v_mov_b32_e32 v252, 0x10000
	v_mov_b32_e32 v253, 0
	global_load_dwordx4 v[232:235], v[64:65], off
	v_lshl_add_u64 v[248:249], v[64:65], 0, v[252:253]
	global_load_dwordx4 v[236:239], v[248:249], off
	v_lshl_add_u64 v[248:249], v[248:249], 0, v[252:253]
	global_load_dwordx4 v[240:243], v[248:249], off
	v_lshl_add_u64 v[248:249], v[248:249], 0, v[252:253]
	global_load_dwordx4 v[244:247], v[248:249], off
	s_waitcnt vmcnt(3)
	v_mov_b32_e32 v66, v232
	v_mov_b32_e32 v67, v233
	v_mov_b32_e32 v68, v234
	v_mov_b32_e32 v69, v235
	v_mov_b32_e32 v64, v68
	v_mov_b32_e32 v65, v69
	s_nop 0
	v_permlane16_swap_b32_e32 v66, v64
	v_permlane16_swap_b32_e32 v67, v65
	s_and_b64 vcc, exec, s[12:13]
	s_cbranch_vccnz .LBB0_544

; __device__ __forceinline__ void unwiden16(const i32x4 w, u32x2& g0, u32x2& g1) {
;   auto r0 = __builtin_amdgcn_permlane16_swap((unsigned)w[0], (unsigned)w[2], false, false);
;   auto r1 = __builtin_amdgcn_permlane16_swap((unsigned)w[1], (unsigned)w[3], false, false);
;   g0[0] = r0[0]; g0[1] = r1[0]; g1[0] = r0[1]; g1[1] = r1[1];
; }
; template <int EPI, int MB, int NB> ...
;     ...
;     for (int m = 0; m < MB; ++m) {
;       const int lr = lrow0 + m * 16;
;       float sq = 0.f;
;       u32x2 ob[2], rw[2];
;       if (rb) unwiden16(*(const i32x4*)(e.resb + (size_t)(brow + lr) * DM + colw), rw[0], rw[1]);
.LBB0_552:
	s_or_b64 exec, exec, s[70:71]
	v_add_u32_e32 v60, 16, v80
	s_and_b64 vcc, exec, s[12:13]
	v_add_u32_e32 v70, s64, v60
	s_cbranch_vccnz .LBB0_554
	v_ashrrev_i32_e32 v71, 31, v70
	s_waitcnt lgkmcnt(0)
	v_lshlrev_b64 v[56:57], 12, v[70:71]
	v_lshl_add_u64 v[56:57], s[54:55], 0, v[56:57]
	v_lshl_add_u64 v[56:57], v[76:77], 1, v[56:57]
	s_waitcnt vmcnt(3)
	v_mov_b32_e32 v66, v236
	v_mov_b32_e32 v67, v237
	v_mov_b32_e32 v68, v238
	v_mov_b32_e32 v69, v239
	v_mov_b32_e32 v56, v68
	v_mov_b32_e32 v57, v69
	s_nop 0
	v_permlane16_swap_b32_e32 v66, v56
	v_permlane16_swap_b32_e32 v67, v57
	v_mov_b32_e32 v64, v56
	v_mov_b32_e32 v65, v57

; __device__ __forceinline__ void unwiden16(const i32x4 w, u32x2& g0, u32x2& g1) {
;   auto r0 = __builtin_amdgcn_permlane16_swap((unsigned)w[0], (unsigned)w[2], false, false);
;   auto r1 = __builtin_amdgcn_permlane16_swap((unsigned)w[1], (unsigned)w[3], false, false);
;   g0[0] = r0[0]; g0[1] = r1[0]; g1[0] = r0[1]; g1[1] = r1[1];
; }
; template <int EPI, int MB, int NB> ...
;     ...
;     for (int m = 0; m < MB; ++m) {
;       const int lr = lrow0 + m * 16;
;       float sq = 0.f;
;       u32x2 ob[2], rw[2];
;       if (rb) unwiden16(*(const i32x4*)(e.resb + (size_t)(brow + lr) * DM + colw), rw[0], rw[1]);
.LBB0_565:
	s_or_b64 exec, exec, s[70:71]
	v_add_u32_e32 v52, 32, v80
	s_and_b64 vcc, exec, s[12:13]
	v_add_u32_e32 v56, s64, v52
	s_cbranch_vccnz .LBB0_567
	v_ashrrev_i32_e32 v57, 31, v56
	s_waitcnt lgkmcnt(0)
	v_lshlrev_b64 v[48:49], 12, v[56:57]
	v_lshl_add_u64 v[48:49], s[54:55], 0, v[48:49]
	v_lshl_add_u64 v[48:49], v[76:77], 1, v[48:49]
	s_waitcnt vmcnt(3)
	v_mov_b32_e32 v66, v240
	v_mov_b32_e32 v67, v241
	v_mov_b32_e32 v68, v242
	v_mov_b32_e32 v69, v243
	v_mov_b32_e32 v48, v68
	v_mov_b32_e32 v49, v69
	s_nop 0
	v_permlane16_swap_b32_e32 v66, v48
	v_permlane16_swap_b32_e32 v67, v49
	v_mov_b32_e32 v64, v48
	v_mov_b32_e32 v65, v49

; __device__ __forceinline__ void unwiden16(const i32x4 w, u32x2& g0, u32x2& g1) {
;   auto r0 = __builtin_amdgcn_permlane16_swap((unsigned)w[0], (unsigned)w[2], false, false);
;   auto r1 = __builtin_amdgcn_permlane16_swap((unsigned)w[1], (unsigned)w[3], false, false);
;   g0[0] = r0[0]; g0[1] = r1[0]; g1[0] = r0[1]; g1[1] = r1[1];
; }
; template <int EPI, int MB, int NB> ...
;     ...
;     for (int m = 0; m < MB; ++m) {
;       const int lr = lrow0 + m * 16;
;       float sq = 0.f;
;       u32x2 ob[2], rw[2];
;       if (rb) unwiden16(*(const i32x4*)(e.resb + (size_t)(brow + lr) * DM + colw), rw[0], rw[1]);
.LBB0_578:
	s_or_b64 exec, exec, s[70:71]
	v_add_u32_e32 v44, 48, v80
	s_and_b64 vcc, exec, s[12:13]
	v_add_u32_e32 v48, s64, v44
	s_cbranch_vccnz .LBB0_580
	v_ashrrev_i32_e32 v49, 31, v48
	s_waitcnt lgkmcnt(0)
	v_lshlrev_b64 v[40:41], 12, v[48:49]
	v_lshl_add_u64 v[40:41], s[54:55], 0, v[40:41]
	v_lshl_add_u64 v[40:41], v[76:77], 1, v[40:41]
	s_waitcnt vmcnt(3)
	v_mov_b32_e32 v66, v244
	v_mov_b32_e32 v67, v245
	v_mov_b32_e32 v68, v246
	v_mov_b32_e32 v69, v247
	v_mov_b32_e32 v40, v68
	v_mov_b32_e32 v41, v69
	s_nop 0
	v_permlane16_swap_b32_e32 v66, v40
	v_permlane16_swap_b32_e32 v67, v41
	v_mov_b32_e32 v64, v40
	v_mov_b32_e32 v65, v41

; __device__ __forceinline__ void unwiden16(const i32x4 w, u32x2& g0, u32x2& g1) {
;   auto r0 = __builtin_amdgcn_permlane16_swap((unsigned)w[0], (unsigned)w[2], false, false);
;   auto r1 = __builtin_amdgcn_permlane16_swap((unsigned)w[1], (unsigned)w[3], false, false);
;   g0[0] = r0[0]; g0[1] = r1[0]; g1[0] = r0[1]; g1[1] = r1[1];
; }
; template <int EPI, int MB, int NB> ...
;     ...
;     for (int m = 0; m < MB; ++m) {
;       const int lr = lrow0 + m * 16;
;       float sq = 0.f;
;       u32x2 ob[2], rw[2];
;       if (rb) unwiden16(*(const i32x4*)(e.resb + (size_t)(brow + lr) * DM + colw), rw[0], rw[1]);
.LBB0_591:
	s_or_b64 exec, exec, s[70:71]
	v_mov_b32_e32 v32, v212
	v_mov_b32_e32 v48, v213
	s_and_b64 vcc, exec, s[12:13]
	v_add_u32_e32 v46, s66, v32
	v_add_u32_e32 v44, v46, v211
	v_ashrrev_i32_e32 v45, 31, v44
	v_add_u32_e32 v50, s64, v48
	s_cbranch_vccnz .LBB0_595
	v_ashrrev_i32_e32 v51, 31, v50
	s_waitcnt lgkmcnt(0)
	v_lshlrev_b64 v[32:33], 12, v[50:51]
	v_lshl_add_u64 v[32:33], s[54:55], 0, v[32:33]
	v_lshl_add_u64 v[32:33], v[44:45], 1, v[32:33]
	v_mov_b32_e32 v252, 0x10000
	v_mov_b32_e32 v253, 0
	global_load_dwordx4 v[232:235], v[32:33], off
	v_lshl_add_u64 v[248:249], v[32:33], 0, v[252:253]
	global_load_dwordx4 v[236:239], v[248:249], off
	v_lshl_add_u64 v[248:249], v[248:249], 0, v[252:253]
	global_load_dwordx4 v[240:243], v[248:249], off
	v_lshl_add_u64 v[248:249], v[248:249], 0, v[252:253]
	global_load_dwordx4 v[244:247], v[248:249], off
	s_waitcnt vmcnt(3)
	v_mov_b32_e32 v34, v232
	v_mov_b32_e32 v35, v233
	v_mov_b32_e32 v36, v234
	v_mov_b32_e32 v37, v235
	v_mov_b32_e32 v32, v36
	v_mov_b32_e32 v33, v37
	s_nop 0
	v_permlane16_swap_b32_e32 v34, v32
	v_permlane16_swap_b32_e32 v35, v33
	s_and_b64 vcc, exec, s[12:13]
	s_cbranch_vccnz .LBB0_596

; __device__ __forceinline__ void unwiden16(const i32x4 w, u32x2& g0, u32x2& g1) {
;   auto r0 = __builtin_amdgcn_permlane16_swap((unsigned)w[0], (unsigned)w[2], false, false);
;   auto r1 = __builtin_amdgcn_permlane16_swap((unsigned)w[1], (unsigned)w[3], false, false);
;   g0[0] = r0[0]; g0[1] = r1[0]; g1[0] = r0[1]; g1[1] = r1[1];
; }
; template <int EPI, int MB, int NB> ...
;     ...
;     for (int m = 0; m < MB; ++m) {
;       const int lr = lrow0 + m * 16;
;       float sq = 0.f;
;       u32x2 ob[2], rw[2];
;       if (rb) unwiden16(*(const i32x4*)(e.resb + (size_t)(brow + lr) * DM + colw), rw[0], rw[1]);
.LBB0_604:
	s_or_b64 exec, exec, s[66:67]
	v_add_u32_e32 v28, 16, v48
	s_and_b64 vcc, exec, s[12:13]
	v_add_u32_e32 v38, s64, v28
	s_cbranch_vccnz .LBB0_606
	v_ashrrev_i32_e32 v39, 31, v38
	s_waitcnt lgkmcnt(0)
	v_lshlrev_b64 v[24:25], 12, v[38:39]
	v_lshl_add_u64 v[24:25], s[54:55], 0, v[24:25]
	v_lshl_add_u64 v[24:25], v[44:45], 1, v[24:25]
	s_waitcnt vmcnt(3)
	v_mov_b32_e32 v34, v236
	v_mov_b32_e32 v35, v237
	v_mov_b32_e32 v36, v238
	v_mov_b32_e32 v37, v239
	v_mov_b32_e32 v24, v36
	v_mov_b32_e32 v25, v37
	s_nop 0
	v_permlane16_swap_b32_e32 v34, v24
	v_permlane16_swap_b32_e32 v35, v25
	v_mov_b32_e32 v32, v24
	v_mov_b32_e32 v33, v25

; __device__ __forceinline__ void unwiden16(const i32x4 w, u32x2& g0, u32x2& g1) {
;   auto r0 = __builtin_amdgcn_permlane16_swap((unsigned)w[0], (unsigned)w[2], false, false);
;   auto r1 = __builtin_amdgcn_permlane16_swap((unsigned)w[1], (unsigned)w[3], false, false);
;   g0[0] = r0[0]; g0[1] = r1[0]; g1[0] = r0[1]; g1[1] = r1[1];
; }
; template <int EPI, int MB, int NB> ...
;     ...
;     for (int m = 0; m < MB; ++m) {
;       const int lr = lrow0 + m * 16;
;       float sq = 0.f;
;       u32x2 ob[2], rw[2];
;       if (rb) unwiden16(*(const i32x4*)(e.resb + (size_t)(brow + lr) * DM + colw), rw[0], rw[1]);
.LBB0_617:
	s_or_b64 exec, exec, s[66:67]
	v_add_u32_e32 v20, 32, v48
	s_and_b64 vcc, exec, s[12:13]
	v_add_u32_e32 v24, s64, v20
	s_cbranch_vccnz .LBB0_619
	v_ashrrev_i32_e32 v25, 31, v24
	s_waitcnt lgkmcnt(0)
	v_lshlrev_b64 v[16:17], 12, v[24:25]
	v_lshl_add_u64 v[16:17], s[54:55], 0, v[16:17]
	v_lshl_add_u64 v[16:17], v[44:45], 1, v[16:17]
	s_waitcnt vmcnt(3)
	v_mov_b32_e32 v34, v240
	v_mov_b32_e32 v35, v241
	v_mov_b32_e32 v36, v242
	v_mov_b32_e32 v37, v243
	v_mov_b32_e32 v16, v36
	v_mov_b32_e32 v17, v37
	s_nop 0
	v_permlane16_swap_b32_e32 v34, v16
	v_permlane16_swap_b32_e32 v35, v17
	v_mov_b32_e32 v32, v16
	v_mov_b32_e32 v33, v17

; __device__ __forceinline__ void unwiden16(const i32x4 w, u32x2& g0, u32x2& g1) {
;   auto r0 = __builtin_amdgcn_permlane16_swap((unsigned)w[0], (unsigned)w[2], false, false);
;   auto r1 = __builtin_amdgcn_permlane16_swap((unsigned)w[1], (unsigned)w[3], false, false);
;   g0[0] = r0[0]; g0[1] = r1[0]; g1[0] = r0[1]; g1[1] = r1[1];
; }
; template <int EPI, int MB, int NB> ...
;     ...
;     for (int m = 0; m < MB; ++m) {
;       const int lr = lrow0 + m * 16;
;       float sq = 0.f;
;       u32x2 ob[2], rw[2];
;       if (rb) unwiden16(*(const i32x4*)(e.resb + (size_t)(brow + lr) * DM + colw), rw[0], rw[1]);
.LBB0_630:
	s_or_b64 exec, exec, s[66:67]
	v_add_u32_e32 v12, 48, v48
	s_and_b64 vcc, exec, s[12:13]
	v_add_u32_e32 v16, s64, v12
	s_cbranch_vccnz .LBB0_632
	v_ashrrev_i32_e32 v17, 31, v16
	s_waitcnt lgkmcnt(0)
	v_lshlrev_b64 v[8:9], 12, v[16:17]
	v_lshl_add_u64 v[8:9], s[54:55], 0, v[8:9]
	v_lshl_add_u64 v[8:9], v[44:45], 1, v[8:9]
	s_waitcnt vmcnt(3)
	v_mov_b32_e32 v34, v244
	v_mov_b32_e32 v35, v245
	v_mov_b32_e32 v36, v246
	v_mov_b32_e32 v37, v247
	v_mov_b32_e32 v8, v36
	v_mov_b32_e32 v9, v37
	s_nop 0
	v_permlane16_swap_b32_e32 v34, v8
	v_permlane16_swap_b32_e32 v35, v9
	v_mov_b32_e32 v32, v8
	v_mov_b32_e32 v33, v9
